# GEMM phases: the two workgroups resident on one compute unit take tiles of the same weight-column block (runtime-verified permutation of workgroup ids, identity fallback)
# speedup vs baseline: 1.0416x; 1.0129x over previous
; #define LAS __attribute__((address_space(3)))
; __global__ void __launch_bounds__(256, 2) mk(Params p_in, int ph_lo, int ph_hi) {
;     ...
;   cg::grid_group grid = cg::this_grid();
;   if (threadIdx.x == 0) sh_misc[0] = make_uint4(0u, 0u, 0u, 0u);
;   __syncthreads();
;   const XcdBarrier xb = xcd_barrier_post((unsigned*)(p_in.ws + OFF_BAR), (volatile LAS unsigned*)&sh_misc[0]);
;   grid.sync();
;   for (int ph = ph_lo; ph < ph_hi; ++ph) {
.LBB0_15:
	s_or_b64 exec, exec, s[6:7]
	s_getreg_b32 s3, hwreg(HW_REG_HW_ID)
	s_bfe_u32 s3, s3, 0x80008
	s_and_b32 s6, s88, 7
	s_lshl_b32 s6, s6, 7
	s_lshr_b32 s7, s3, 3
	s_lshl_b32 s7, s7, 2
	s_add_u32 s6, s6, s7
	s_and_b32 s7, s3, 7
	s_lshl_b32 s7, s7, 2
	s_lshl_b32 s10, 1, s7
	s_add_u32 s12, s84, 0xfd16600
	s_addc_u32 s13, s85, 0
	v_mov_b32_e32 v2, s6
	v_mov_b32_e32 v3, s10
	s_and_saveexec_b64 s[10:11], s[58:59]
	s_cbranch_execz .Lmy_pair_reg
	global_atomic_add v4, v2, v3, s[12:13] sc0
	s_waitcnt vmcnt(0)
	v_lshrrev_b32_e32 v4, s7, v4
	v_and_b32_e32 v4, 15, v4
	v_mov_b32_e32 v5, s3
	v_mov_b32_e32 v2, 0
	ds_write_b64 v2, v[4:5] offset:24
	s_waitcnt lgkmcnt(0)
.Lmy_pair_reg:
	s_or_b64 exec, exec, s[10:11]
	s_load_dwordx2 s[86:87], s[0:1], 0xb8
	s_barrier
	s_waitcnt lgkmcnt(0)
	v_mov_b32_e32 v2, 0
	ds_read_b64 v[4:5], v2 offset:24
	s_waitcnt lgkmcnt(0)
	v_readfirstlane_b32 s3, v4
	v_readfirstlane_b32 s6, v5
	v_writelane_b32 v247, s3, 60
	v_writelane_b32 v247, s6, 61
	v_writelane_b32 v247, s88, 62
	s_cmp_ge_i32 s86, s87
	s_cbranch_scc0 .LBB0_16
	s_getpc_b64 s[98:99]

; __global__ void __launch_bounds__(256, 2) mk(Params p_in, int ph_lo, int ph_hi) {
;     ...
;   grid.sync();
;   for (int ph = ph_lo; ph < ph_hi; ++ph) {
.LBB0_19:
	s_cmp_lg_u32 s86, 0
	s_cbranch_scc1 .Lmy_pair_done
	s_and_b32 s98, s88, 7
	s_lshl_b32 s98, s98, 7
	s_add_u32 s100, s84, 0xfd16600
	s_addc_u32 s101, s85, 0
	s_add_u32 s100, s100, s98
	s_addc_u32 s101, s101, 0
	v_mbcnt_lo_u32_b32 v2, -1, 0
	v_mbcnt_hi_u32_b32 v2, -1, v2
	v_lshlrev_b32_e32 v3, 2, v2
	global_load_dword v4, v3, s[100:101]
	v_readlane_b32 s98, v247, 61
	s_lshr_b32 s99, s98, 3
	s_and_b32 s98, s98, 7
	s_lshl_b32 s98, s98, 2
	s_lshl_b32 s98, 1, s98
	s_sub_u32 s98, s98, 1
	s_waitcnt vmcnt(0)
	v_lshrrev_b32_e32 v5, 1, v4
	v_or_b32_e32 v5, v5, v4
	v_lshrrev_b32_e32 v6, 2, v5
	v_or_b32_e32 v5, v5, v6
	v_and_b32_e32 v5, 0x11111111, v5
	v_bcnt_u32_b32 v6, v5, 0
	v_and_b32_e32 v7, s98, v5
	v_bcnt_u32_b32 v7, v7, 0
	v_cmp_gt_u32_e32 vcc, s99, v2
	v_cndmask_b32_e32 v8, 0, v6, vcc
	v_cmp_eq_u32_e32 vcc, s99, v2
	v_cndmask_b32_e32 v8, v8, v7, vcc
	v_and_b32_e32 v9, 0xdddddddd, v4
	v_cmp_ne_u32_e32 vcc, 0, v9
	v_cndmask_b32_e64 v9, 0, 1, vcc
	v_lshl_or_b32 v8, v6, 10, v8
	v_lshl_or_b32 v8, v9, 20, v8
	s_mov_b32 s99, 0
	s_mov_b32 s100, 0
.Lmy_pair_sum:
	s_nop 3
	v_readlane_b32 s98, v8, s99
	s_add_u32 s100, s100, s98
	s_add_u32 s99, s99, 1
	s_cmp_lt_u32 s99, 32
	s_cbranch_scc1 .Lmy_pair_sum
	s_lshr_b32 s98, s100, 10
	s_cmp_lg_u32 s98, 32
	s_cbranch_scc1 .Lmy_pair_done
	s_and_b32 s100, s100, 0x3ff
	v_readlane_b32 s98, v247, 60
	s_lshl_b32 s98, s98, 5
	s_add_u32 s100, s100, s98
	s_lshl_b32 s100, s100, 3
	s_and_b32 s98, s88, 7
	s_or_b32 s100, s100, s98
	v_writelane_b32 v247, s100, 62

; #define BIDX opaque_bid()
;   const int nmain = 64 * nnt, ntiles = nmain + nnt;
;   const int nb = gridDim.x - skip;
;   const int b = BIDX - skip;
;   const bool xmap = (skip == 0) && ((nnt & 7) == 0) && ((nb & 63) == 0);
;   const int q = xmap ? (b & 7) * (nb >> 3) + (b >> 3) : b;
.LBB0_30:
	s_and_b64 vcc, exec, s[6:7]
	s_cbranch_vccz .LBB0_299
	v_readlane_b32 s0, v247, 22
	s_cmp_gt_i32 s0, 0
	s_cbranch_scc0 .LBB0_67
	s_cmp_gt_i32 s0, 1
	s_cbranch_scc0 .LBB0_68
	s_mov_b64 s[6:7], 0
	s_cmp_eq_u32 s0, 2
	s_mov_b64 s[0:1], 0
	s_cbranch_scc0 .LBB0_69
	v_readlane_b32 s0, v249, 48
	v_readlane_b32 s1, v249, 49
	v_readlane_b32 s5, v247, 62
	s_andn2_b64 vcc, exec, s[0:1]
	s_cbranch_vccnz .LBB0_36
	s_and_b32 s0, s5, 7
	s_mul_i32 s0, s0, s92
	s_ashr_i32 s1, s5, 3
	s_add_i32 s5, s0, s1

; #define BIDX opaque_bid()
;   const int nmain = 64 * nnt, ntiles = nmain + nnt;
;   const int nb = gridDim.x - skip;
;   const int b = BIDX - skip;
;   const bool xmap = (skip == 0) && ((nnt & 7) == 0) && ((nb & 63) == 0);
;   const int q = xmap ? (b & 7) * (nb >> 3) + (b >> 3) : b;
.LBB0_307:
	s_and_b64 vcc, exec, s[6:7]
	s_cbranch_vccz .LBB0_343
	v_readlane_b32 s5, v247, 22
	s_cmp_lt_i32 s5, 6
	s_mov_b64 s[6:7], -1
	s_cbranch_scc0 .LBB0_342
	v_readlane_b32 s0, v249, 48
	v_readlane_b32 s1, v249, 49
	v_readlane_b32 s5, v247, 62
	s_andn2_b64 vcc, exec, s[0:1]
	s_cbranch_vccnz .LBB0_311
	s_and_b32 s0, s5, 7
	s_mul_i32 s0, s0, s92
	s_ashr_i32 s1, s5, 3
	s_add_i32 s5, s0, s1

; #define BIDX opaque_bid()
;   const int nmain = 64 * nnt, ntiles = nmain + nnt;
;   const int nb = gridDim.x - skip;
;   const int b = BIDX - skip;
;   const bool xmap = (skip == 0) && ((nnt & 7) == 0) && ((nb & 63) == 0);
;   const int q = xmap ? (b & 7) * (nb >> 3) + (b >> 3) : b;
.LBB0_380:
	v_readlane_b32 s0, v249, 48
	v_readlane_b32 s1, v249, 49
	v_readlane_b32 s5, v247, 62
	s_andn2_b64 vcc, exec, s[0:1]
	s_cbranch_vccnz .LBB0_382
	s_and_b32 s0, s5, 7
	s_mul_i32 s0, s0, s92
	s_ashr_i32 s1, s5, 3
	s_add_i32 s5, s0, s1

; #define BIDX opaque_bid()
;   const int nmain = 64 * nnt, ntiles = nmain + nnt;
;   const int nb = gridDim.x - skip;
;   const int b = BIDX - skip;
;   const bool xmap = (skip == 0) && ((nnt & 7) == 0) && ((nb & 63) == 0);
;   const int q = xmap ? (b & 7) * (nb >> 3) + (b >> 3) : b;
.LBB0_1344:
	s_andn2_b64 vcc, exec, s[6:7]
	s_cbranch_vccnz .LBB0_1572
	v_readlane_b32 s5, v247, 22
	s_cmp_eq_u32 s5, 0
	s_cbranch_scc0 .LBB0_1572
	s_add_u32 s6, s14, 0x3a91000
	s_addc_u32 s7, s15, 0
	v_readlane_b32 s5, v247, 62
	s_mov_b32 s9, 0
	s_branch .LBB0_1350

; #define BIDX opaque_bid()
;   const int nmain = 64 * nnt, ntiles = nmain + nnt;
;   const int nb = gridDim.x - skip;
;   const int b = BIDX - skip;
;   const bool xmap = (skip == 0) && ((nnt & 7) == 0) && ((nb & 63) == 0);
;   const int q = xmap ? (b & 7) * (nb >> 3) + (b >> 3) : b;
.LBB0_1822:
	v_readlane_b32 s0, v247, 32
	v_readlane_b32 s1, v247, 33
	s_and_b64 vcc, exec, s[0:1]
	v_cmp_ne_u32_e64 s[36:37], 1, v207
	s_cbranch_vccz .LBB0_1855
	v_readlane_b32 s5, v247, 62
	s_and_b64 vcc, exec, s[36:37]
	s_cbranch_vccnz .LBB0_1825
	s_and_b32 s0, s5, 7
	s_mul_i32 s0, s0, s92
	s_ashr_i32 s1, s5, 3
	s_add_i32 s5, s0, s1

; #define BIDX opaque_bid()
;   const int nmain = 64 * nnt, ntiles = nmain + nnt;
;   const int nb = gridDim.x - skip;
;   const int b = BIDX - skip;
;   const bool xmap = (skip == 0) && ((nnt & 7) == 0) && ((nb & 63) == 0);
;   const int q = xmap ? (b & 7) * (nb >> 3) + (b >> 3) : b;
.LBB0_1857:
	s_andn2_b64 vcc, exec, s[6:7]
	v_readlane_b32 s6, v247, 28
	v_readlane_b32 s7, v247, 29
	s_cbranch_vccnz .LBB0_1891
	v_readlane_b32 s5, v247, 62
	s_and_b64 vcc, exec, s[36:37]
	s_cbranch_vccnz .LBB0_1860
	s_and_b32 s0, s5, 7
	s_mul_i32 s0, s0, s92
	s_ashr_i32 s1, s5, 3
	s_add_i32 s5, s0, s1

; __global__ void __launch_bounds__(256, 2) mk(Params p_in, int ph_lo, int ph_hi) {
	.amdhsa_kernel _Z2mk6Paramsii
		.amdhsa_group_segment_fixed_size 32
		.amdhsa_private_segment_fixed_size 0
		.amdhsa_kernarg_size 448
		.amdhsa_user_sgpr_count 2
		.amdhsa_user_sgpr_dispatch_ptr 0
		.amdhsa_user_sgpr_queue_ptr 0
		.amdhsa_user_sgpr_kernarg_segment_ptr 1
		.amdhsa_user_sgpr_dispatch_id 0
		.amdhsa_user_sgpr_kernarg_preload_length 0
		.amdhsa_user_sgpr_kernarg_preload_offset 0
		.amdhsa_user_sgpr_private_segment_size 0
		.amdhsa_uses_dynamic_stack 0
		.amdhsa_enable_private_segment 0
		.amdhsa_system_sgpr_workgroup_id_x 1
		.amdhsa_system_sgpr_workgroup_id_y 0
		.amdhsa_system_sgpr_workgroup_id_z 0
		.amdhsa_system_sgpr_workgroup_info 0
		.amdhsa_system_vgpr_workitem_id 2
		.amdhsa_next_free_vgpr 250
		.amdhsa_next_free_sgpr 102
		.amdhsa_accum_offset 252
		.amdhsa_reserve_vcc 1
		.amdhsa_float_round_mode_32 0
		.amdhsa_float_round_mode_16_64 0
		.amdhsa_float_denorm_mode_32 3
		.amdhsa_float_denorm_mode_16_64 3
		.amdhsa_dx10_clamp 1
		.amdhsa_ieee_mode 1
		.amdhsa_fp16_overflow 0
		.amdhsa_tg_split 0
		.amdhsa_exception_fp_ieee_invalid_op 0
		.amdhsa_exception_fp_denorm_src 0
		.amdhsa_exception_fp_ieee_div_zero 0
		.amdhsa_exception_fp_ieee_overflow 0
		.amdhsa_exception_fp_ieee_underflow 0
		.amdhsa_exception_fp_ieee_inexact 0
		.amdhsa_exception_int_div_zero 0
	.end_amdhsa_kernel

; __global__ void __launch_bounds__(256, 2) mk(Params p_in, int ph_lo, int ph_hi) {
amdhsa.kernels:
  - .agpr_count:     0
    .args:
      - .offset:         0
        .size:           184
        .value_kind:     by_value
      - .offset:         184
        .size:           4
        .value_kind:     by_value
      - .offset:         188
        .size:           4
        .value_kind:     by_value
      - .offset:         192
        .size:           4
        .value_kind:     hidden_block_count_x
      - .offset:         196
        .size:           4
        .value_kind:     hidden_block_count_y
      - .offset:         200
        .size:           4
        .value_kind:     hidden_block_count_z
      - .offset:         204
        .size:           2
        .value_kind:     hidden_group_size_x
      - .offset:         206
        .size:           2
        .value_kind:     hidden_group_size_y
      - .offset:         208
        .size:           2
        .value_kind:     hidden_group_size_z
      - .offset:         210
        .size:           2
        .value_kind:     hidden_remainder_x
      - .offset:         212
        .size:           2
        .value_kind:     hidden_remainder_y
      - .offset:         214
        .size:           2
        .value_kind:     hidden_remainder_z
      - .offset:         232
        .size:           8
        .value_kind:     hidden_global_offset_x
      - .offset:         240
        .size:           8
        .value_kind:     hidden_global_offset_y
      - .offset:         248
        .size:           8
        .value_kind:     hidden_global_offset_z
      - .offset:         256
        .size:           2
        .value_kind:     hidden_grid_dims
      - .offset:         280
        .size:           8
        .value_kind:     hidden_multigrid_sync_arg
      - .offset:         312
        .size:           4
        .value_kind:     hidden_dynamic_lds_size
    .group_segment_fixed_size: 32
    .kernarg_segment_align: 8
    .kernarg_segment_size: 448
    .language:       OpenCL C
    .language_version:
      - 2
      - 0
    .max_flat_workgroup_size: 256
    .name:           _Z2mk6Paramsii
    .private_segment_fixed_size: 0
    .sgpr_count:     108
    .sgpr_spill_count: 222
    .symbol:         _Z2mk6Paramsii.kd
    .uniform_work_group_size: 1
    .uses_dynamic_stack: false
    .vgpr_count:     250
    .vgpr_spill_count: 0
    .wavefront_size: 64
